# GEMM phases with a per-row rstd table: the sum-of-squares loads of the workgroup's units issued back to back and converted together before the barrier (was load + vmcnt(0) + rsqrt per unit)
# baseline (speedup 1.0000x reference)
.LBB0_72:
	s_add_i32 s4, 16, 0x20000
	s_lshl_b32 s10, s24, 3
	v_lshl_add_u32 v10, v12, 2, s4
	s_movk_i32 s4, 0x100
	s_cmp_eq_u32 s70, 4
	v_cmp_gt_i32_e64 s[36:37], s4, v12
	s_cselect_b64 s[4:5], -1, 0
	s_and_saveexec_b64 s[6:7], s[36:37]
	s_cbranch_execz .LBB0_74
	v_cvt_f32_u32_e32 v11, s10
	s_sub_i32 s17, 0, s10
	s_ashr_i32 s8, s8, 3
	s_add_i32 s8, s9, s8
	v_rcp_iflag_f32_e32 v11, v11
	s_abs_i32 s18, s8
	s_ashr_i32 s9, s8, 31
	s_mov_b32 s2, 0x800000
	v_mul_f32_e32 v11, 0x4f7ffffe, v11
	v_cvt_u32_f32_e32 v11, v11
	s_nop 0
	v_readfirstlane_b32 s19, v11
	s_mul_i32 s17, s17, s19
	s_mul_hi_u32 s17, s19, s17
	s_add_i32 s19, s19, s17
	s_mul_hi_u32 s17, s18, s19
	s_mul_i32 s19, s17, s10
	s_sub_i32 s18, s18, s19
	s_add_i32 s21, s17, 1
	s_sub_i32 s19, s18, s10
	s_cmp_ge_u32 s18, s10
	s_cselect_b32 s17, s21, s17
	s_cselect_b32 s18, s19, s18
	s_add_i32 s19, s17, 1
	s_cmp_ge_u32 s18, s10
	s_cselect_b32 s17, s19, s17
	s_xor_b32 s17, s17, s9
	s_sub_i32 s9, s17, s9
	s_lshl_b32 s18, s9, 3
	s_mul_i32 s17, s9, s10
	s_sub_i32 s9, s88, s18
	s_min_i32 s19, s9, 8
	s_sext_i32_i16 s9, s19
	v_cvt_f32_i32_e32 v11, s9
	s_sub_i32 s17, s8, s17
	s_sext_i32_i16 s8, s17
	v_cvt_f32_i32_e32 v13, s8
	v_rcp_iflag_f32_e32 v14, v11
	s_xor_b32 s8, s8, s9
	s_ashr_i32 s8, s8, 30
	s_or_b32 s21, s8, 1
	v_mul_f32_e32 v14, v13, v14
	v_trunc_f32_e32 v14, v14
	v_fma_f32 v13, -v14, v11, v13
	v_cvt_i32_f32_e32 v14, v14
	v_cmp_ge_f32_e64 s[8:9], |v13|, |v11|
	s_and_b64 s[8:9], s[8:9], exec
	s_cselect_b32 s8, s21, 0
	v_readfirstlane_b32 s9, v14
	s_add_i32 s8, s9, s8
	s_sext_i32_i16 s21, s8
	s_mul_i32 s8, s8, s19
	s_sub_i32 s8, s17, s8
	s_sext_i32_i16 s8, s8
	s_add_i32 s18, s18, s8
	s_and_b64 s[8:9], s[4:5], exec
	s_cselect_b32 s8, s21, s18
	v_lshl_add_u32 v14, s8, 8, v12
	v_ashrrev_i32_e32 v15, 31, v14
	v_lshl_add_u64 v[14:15], v[14:15], 2, s[0:1]
	global_load_dword v128, v[14:15], off

.LBB0_78:
	v_cvt_f32_u32_e32 v11, s10
	s_sub_i32 s19, 0, s10
	s_ashr_i32 s17, s17, 3
	s_add_i32 s17, s18, s17
	v_rcp_iflag_f32_e32 v11, v11
	s_abs_i32 s21, s17
	s_ashr_i32 s18, s17, 31
	s_mov_b32 s2, 0x800000
	v_mul_f32_e32 v11, 0x4f7ffffe, v11
	v_cvt_u32_f32_e32 v11, v11
	s_nop 0
	v_readfirstlane_b32 s26, v11
	s_mul_i32 s19, s19, s26
	s_mul_hi_u32 s19, s26, s19
	s_add_i32 s26, s26, s19
	s_mul_hi_u32 s19, s21, s26
	s_mul_i32 s26, s19, s10
	s_sub_i32 s21, s21, s26
	s_add_i32 s27, s19, 1
	s_sub_i32 s26, s21, s10
	s_cmp_ge_u32 s21, s10
	s_cselect_b32 s19, s27, s19
	s_cselect_b32 s21, s26, s21
	s_add_i32 s26, s19, 1
	s_cmp_ge_u32 s21, s10
	s_cselect_b32 s19, s26, s19
	s_xor_b32 s19, s19, s18
	s_sub_i32 s18, s19, s18
	s_lshl_b32 s19, s18, 3
	s_sub_i32 s21, s88, s19
	s_min_i32 s21, s21, 8
	s_abs_i32 s26, s21
	v_cvt_f32_u32_e32 v11, s26
	s_sub_i32 s30, 0, s26
	s_mul_i32 s18, s18, s10
	s_sub_i32 s17, s17, s18
	v_rcp_iflag_f32_e32 v11, v11
	s_abs_i32 s18, s17
	s_xor_b32 s27, s17, s21
	s_ashr_i32 s27, s27, 31
	v_mul_f32_e32 v11, 0x4f7ffffe, v11
	v_cvt_u32_f32_e32 v11, v11
	s_nop 0
	v_readfirstlane_b32 s31, v11
	s_mul_i32 s30, s30, s31
	s_mul_hi_u32 s30, s31, s30
	s_add_i32 s31, s31, s30
	s_mul_hi_u32 s30, s18, s31
	s_mul_i32 s31, s30, s26
	s_sub_i32 s18, s18, s31
	s_add_i32 s34, s30, 1
	s_sub_i32 s31, s18, s26
	s_cmp_ge_u32 s18, s26
	s_cselect_b32 s30, s34, s30
	s_cselect_b32 s18, s31, s18
	s_add_i32 s31, s30, 1
	s_cmp_ge_u32 s18, s26
	s_cselect_b32 s18, s31, s30
	s_xor_b32 s18, s18, s27
	s_sub_i32 s26, s18, s27
	s_mul_i32 s18, s26, s21
	s_sub_i32 s17, s17, s18
	s_add_i32 s17, s17, s19
	s_and_b64 s[18:19], s[4:5], exec
	s_cselect_b32 s17, s26, s17
	v_lshl_add_u32 v14, s17, 8, v12
	v_ashrrev_i32_e32 v15, 31, v14
	v_lshl_add_u64 v[14:15], v[14:15], 2, s[0:1]
	global_load_dword v129, v[14:15], off

.LBB0_83:
	v_cvt_f32_u32_e32 v11, s10
	s_sub_i32 s19, 0, s10
	s_ashr_i32 s17, s17, 3
	s_add_i32 s17, s18, s17
	v_rcp_iflag_f32_e32 v11, v11
	s_abs_i32 s21, s17
	s_ashr_i32 s18, s17, 31
	s_mov_b32 s2, 0x800000
	v_mul_f32_e32 v11, 0x4f7ffffe, v11
	v_cvt_u32_f32_e32 v11, v11
	s_nop 0
	v_readfirstlane_b32 s26, v11
	s_mul_i32 s19, s19, s26
	s_mul_hi_u32 s19, s26, s19
	s_add_i32 s26, s26, s19
	s_mul_hi_u32 s19, s21, s26
	s_mul_i32 s26, s19, s10
	s_sub_i32 s21, s21, s26
	s_add_i32 s27, s19, 1
	s_sub_i32 s26, s21, s10
	s_cmp_ge_u32 s21, s10
	s_cselect_b32 s19, s27, s19
	s_cselect_b32 s21, s26, s21
	s_add_i32 s26, s19, 1
	s_cmp_ge_u32 s21, s10
	s_cselect_b32 s19, s26, s19
	s_xor_b32 s19, s19, s18
	s_sub_i32 s18, s19, s18
	s_lshl_b32 s19, s18, 3
	s_sub_i32 s21, s88, s19
	s_min_i32 s21, s21, 8
	s_abs_i32 s26, s21
	v_cvt_f32_u32_e32 v11, s26
	s_sub_i32 s30, 0, s26
	s_mul_i32 s18, s18, s10
	s_sub_i32 s17, s17, s18
	v_rcp_iflag_f32_e32 v11, v11
	s_abs_i32 s18, s17
	s_xor_b32 s27, s17, s21
	s_ashr_i32 s27, s27, 31
	v_mul_f32_e32 v11, 0x4f7ffffe, v11
	v_cvt_u32_f32_e32 v11, v11
	s_nop 0
	v_readfirstlane_b32 s31, v11
	s_mul_i32 s30, s30, s31
	s_mul_hi_u32 s30, s31, s30
	s_add_i32 s31, s31, s30
	s_mul_hi_u32 s30, s18, s31
	s_mul_i32 s31, s30, s26
	s_sub_i32 s18, s18, s31
	s_add_i32 s34, s30, 1
	s_sub_i32 s31, s18, s26
	s_cmp_ge_u32 s18, s26
	s_cselect_b32 s30, s34, s30
	s_cselect_b32 s18, s31, s18
	s_add_i32 s31, s30, 1
	s_cmp_ge_u32 s18, s26
	s_cselect_b32 s18, s31, s30
	s_xor_b32 s18, s18, s27
	s_sub_i32 s26, s18, s27
	s_mul_i32 s18, s26, s21
	s_sub_i32 s17, s17, s18
	s_add_i32 s17, s17, s19
	s_and_b64 s[18:19], s[4:5], exec
	s_cselect_b32 s17, s26, s17
	v_lshl_add_u32 v14, s17, 8, v12
	v_ashrrev_i32_e32 v15, 31, v14
	v_lshl_add_u64 v[14:15], v[14:15], 2, s[0:1]
	global_load_dword v130, v[14:15], off

.LBB0_88:
	v_cvt_f32_u32_e32 v11, s10
	s_sub_i32 s19, 0, s10
	s_ashr_i32 s17, s17, 3
	s_add_i32 s17, s18, s17
	v_rcp_iflag_f32_e32 v11, v11
	s_abs_i32 s21, s17
	s_ashr_i32 s18, s17, 31
	s_mov_b32 s2, 0x800000
	v_mul_f32_e32 v11, 0x4f7ffffe, v11
	v_cvt_u32_f32_e32 v11, v11
	s_nop 0
	v_readfirstlane_b32 s26, v11
	s_mul_i32 s19, s19, s26
	s_mul_hi_u32 s19, s26, s19
	s_add_i32 s26, s26, s19
	s_mul_hi_u32 s19, s21, s26
	s_mul_i32 s26, s19, s10
	s_sub_i32 s21, s21, s26
	s_add_i32 s27, s19, 1
	s_sub_i32 s26, s21, s10
	s_cmp_ge_u32 s21, s10
	s_cselect_b32 s19, s27, s19
	s_cselect_b32 s21, s26, s21
	s_add_i32 s26, s19, 1
	s_cmp_ge_u32 s21, s10
	s_cselect_b32 s19, s26, s19
	s_xor_b32 s19, s19, s18
	s_sub_i32 s18, s19, s18
	s_lshl_b32 s19, s18, 3
	s_sub_i32 s21, s88, s19
	s_min_i32 s21, s21, 8
	s_abs_i32 s26, s21
	v_cvt_f32_u32_e32 v11, s26
	s_sub_i32 s30, 0, s26
	s_mul_i32 s18, s18, s10
	s_sub_i32 s17, s17, s18
	v_rcp_iflag_f32_e32 v11, v11
	s_abs_i32 s18, s17
	s_xor_b32 s27, s17, s21
	s_ashr_i32 s27, s27, 31
	v_mul_f32_e32 v11, 0x4f7ffffe, v11
	v_cvt_u32_f32_e32 v11, v11
	s_nop 0
	v_readfirstlane_b32 s31, v11
	s_mul_i32 s30, s30, s31
	s_mul_hi_u32 s30, s31, s30
	s_add_i32 s31, s31, s30
	s_mul_hi_u32 s30, s18, s31
	s_mul_i32 s31, s30, s26
	s_sub_i32 s18, s18, s31
	s_add_i32 s34, s30, 1
	s_sub_i32 s31, s18, s26
	s_cmp_ge_u32 s18, s26
	s_cselect_b32 s30, s34, s30
	s_cselect_b32 s18, s31, s18
	s_add_i32 s31, s30, 1
	s_cmp_ge_u32 s18, s26
	s_cselect_b32 s18, s31, s30
	s_xor_b32 s18, s18, s27
	s_sub_i32 s26, s18, s27
	s_mul_i32 s18, s26, s21
	s_sub_i32 s17, s17, s18
	s_add_i32 s17, s17, s19
	s_and_b64 s[18:19], s[4:5], exec
	s_cselect_b32 s17, s26, s17
	v_lshl_add_u32 v14, s17, 8, v12
	v_ashrrev_i32_e32 v15, 31, v14
	v_lshl_add_u64 v[14:15], v[14:15], 2, s[0:1]
	global_load_dword v131, v[14:15], off

.LBB0_93:
	v_cvt_f32_u32_e32 v11, s10
	s_sub_i32 s19, 0, s10
	s_ashr_i32 s17, s17, 3
	s_add_i32 s17, s18, s17
	v_rcp_iflag_f32_e32 v11, v11
	s_abs_i32 s21, s17
	s_ashr_i32 s18, s17, 31
	s_mov_b32 s2, 0x800000
	v_mul_f32_e32 v11, 0x4f7ffffe, v11
	v_cvt_u32_f32_e32 v11, v11
	s_nop 0
	v_readfirstlane_b32 s26, v11
	s_mul_i32 s19, s19, s26
	s_mul_hi_u32 s19, s26, s19
	s_add_i32 s26, s26, s19
	s_mul_hi_u32 s19, s21, s26
	s_mul_i32 s26, s19, s10
	s_sub_i32 s21, s21, s26
	s_add_i32 s27, s19, 1
	s_sub_i32 s26, s21, s10
	s_cmp_ge_u32 s21, s10
	s_cselect_b32 s19, s27, s19
	s_cselect_b32 s21, s26, s21
	s_add_i32 s26, s19, 1
	s_cmp_ge_u32 s21, s10
	s_cselect_b32 s19, s26, s19
	s_xor_b32 s19, s19, s18
	s_sub_i32 s18, s19, s18
	s_lshl_b32 s19, s18, 3
	s_sub_i32 s21, s88, s19
	s_min_i32 s21, s21, 8
	s_abs_i32 s26, s21
	v_cvt_f32_u32_e32 v11, s26
	s_sub_i32 s30, 0, s26
	s_mul_i32 s18, s18, s10
	s_sub_i32 s17, s17, s18
	v_rcp_iflag_f32_e32 v11, v11
	s_abs_i32 s18, s17
	s_xor_b32 s27, s17, s21
	s_ashr_i32 s27, s27, 31
	v_mul_f32_e32 v11, 0x4f7ffffe, v11
	v_cvt_u32_f32_e32 v11, v11
	s_nop 0
	v_readfirstlane_b32 s31, v11
	s_mul_i32 s30, s30, s31
	s_mul_hi_u32 s30, s31, s30
	s_add_i32 s31, s31, s30
	s_mul_hi_u32 s30, s18, s31
	s_mul_i32 s31, s30, s26
	s_sub_i32 s18, s18, s31
	s_add_i32 s34, s30, 1
	s_sub_i32 s31, s18, s26
	s_cmp_ge_u32 s18, s26
	s_cselect_b32 s30, s34, s30
	s_cselect_b32 s18, s31, s18
	s_add_i32 s31, s30, 1
	s_cmp_ge_u32 s18, s26
	s_cselect_b32 s18, s31, s30
	s_xor_b32 s18, s18, s27
	s_sub_i32 s26, s18, s27
	s_mul_i32 s18, s26, s21
	s_sub_i32 s17, s17, s18
	s_add_i32 s17, s17, s19
	s_and_b64 s[18:19], s[4:5], exec
	s_cselect_b32 s17, s26, s17
	v_lshl_add_u32 v14, s17, 8, v12
	v_ashrrev_i32_e32 v15, 31, v14
	v_lshl_add_u64 v[14:15], v[14:15], 2, s[0:1]
	global_load_dword v132, v[14:15], off

.LBB0_98:
	v_cvt_f32_u32_e32 v11, s10
	s_sub_i32 s19, 0, s10
	s_ashr_i32 s17, s17, 3
	s_add_i32 s17, s18, s17
	v_rcp_iflag_f32_e32 v11, v11
	s_abs_i32 s21, s17
	s_ashr_i32 s18, s17, 31
	s_mov_b32 s2, 0x800000
	v_mul_f32_e32 v11, 0x4f7ffffe, v11
	v_cvt_u32_f32_e32 v11, v11
	s_nop 0
	v_readfirstlane_b32 s26, v11
	s_mul_i32 s19, s19, s26
	s_mul_hi_u32 s19, s26, s19
	s_add_i32 s26, s26, s19
	s_mul_hi_u32 s19, s21, s26
	s_mul_i32 s26, s19, s10
	s_sub_i32 s21, s21, s26
	s_add_i32 s27, s19, 1
	s_sub_i32 s26, s21, s10
	s_cmp_ge_u32 s21, s10
	s_cselect_b32 s19, s27, s19
	s_cselect_b32 s21, s26, s21
	s_add_i32 s26, s19, 1
	s_cmp_ge_u32 s21, s10
	s_cselect_b32 s19, s26, s19
	s_xor_b32 s19, s19, s18
	s_sub_i32 s18, s19, s18
	s_lshl_b32 s19, s18, 3
	s_sub_i32 s21, s88, s19
	s_min_i32 s21, s21, 8
	s_abs_i32 s26, s21
	v_cvt_f32_u32_e32 v11, s26
	s_sub_i32 s30, 0, s26
	s_mul_i32 s18, s18, s10
	s_sub_i32 s17, s17, s18
	v_rcp_iflag_f32_e32 v11, v11
	s_abs_i32 s18, s17
	s_xor_b32 s27, s17, s21
	s_ashr_i32 s27, s27, 31
	v_mul_f32_e32 v11, 0x4f7ffffe, v11
	v_cvt_u32_f32_e32 v11, v11
	s_nop 0
	v_readfirstlane_b32 s31, v11
	s_mul_i32 s30, s30, s31
	s_mul_hi_u32 s30, s31, s30
	s_add_i32 s31, s31, s30
	s_mul_hi_u32 s30, s18, s31
	s_mul_i32 s31, s30, s26
	s_sub_i32 s18, s18, s31
	s_add_i32 s34, s30, 1
	s_sub_i32 s31, s18, s26
	s_cmp_ge_u32 s18, s26
	s_cselect_b32 s30, s34, s30
	s_cselect_b32 s18, s31, s18
	s_add_i32 s31, s30, 1
	s_cmp_ge_u32 s18, s26
	s_cselect_b32 s18, s31, s30
	s_xor_b32 s18, s18, s27
	s_sub_i32 s26, s18, s27
	s_mul_i32 s18, s26, s21
	s_sub_i32 s17, s17, s18
	s_add_i32 s17, s17, s19
	s_and_b64 s[18:19], s[4:5], exec
	s_cselect_b32 s17, s26, s17
	v_lshl_add_u32 v14, s17, 8, v12
	v_ashrrev_i32_e32 v15, 31, v14
	v_lshl_add_u64 v[14:15], v[14:15], 2, s[0:1]
	global_load_dword v133, v[14:15], off

.LBB0_103:
	v_cvt_f32_u32_e32 v11, s10
	s_sub_i32 s19, 0, s10
	s_ashr_i32 s17, s17, 3
	s_add_i32 s17, s18, s17
	v_rcp_iflag_f32_e32 v11, v11
	s_abs_i32 s21, s17
	s_ashr_i32 s18, s17, 31
	s_mov_b32 s2, 0x800000
	v_mul_f32_e32 v11, 0x4f7ffffe, v11
	v_cvt_u32_f32_e32 v11, v11
	s_nop 0
	v_readfirstlane_b32 s26, v11
	s_mul_i32 s19, s19, s26
	s_mul_hi_u32 s19, s26, s19
	s_add_i32 s26, s26, s19
	s_mul_hi_u32 s19, s21, s26
	s_mul_i32 s26, s19, s10
	s_sub_i32 s21, s21, s26
	s_add_i32 s27, s19, 1
	s_sub_i32 s26, s21, s10
	s_cmp_ge_u32 s21, s10
	s_cselect_b32 s19, s27, s19
	s_cselect_b32 s21, s26, s21
	s_add_i32 s26, s19, 1
	s_cmp_ge_u32 s21, s10
	s_cselect_b32 s19, s26, s19
	s_xor_b32 s19, s19, s18
	s_sub_i32 s18, s19, s18
	s_lshl_b32 s19, s18, 3
	s_sub_i32 s21, s88, s19
	s_min_i32 s21, s21, 8
	s_abs_i32 s26, s21
	v_cvt_f32_u32_e32 v11, s26
	s_sub_i32 s30, 0, s26
	s_mul_i32 s18, s18, s10
	s_sub_i32 s17, s17, s18
	v_rcp_iflag_f32_e32 v11, v11
	s_abs_i32 s18, s17
	s_xor_b32 s27, s17, s21
	s_ashr_i32 s27, s27, 31
	v_mul_f32_e32 v11, 0x4f7ffffe, v11
	v_cvt_u32_f32_e32 v11, v11
	s_nop 0
	v_readfirstlane_b32 s31, v11
	s_mul_i32 s30, s30, s31
	s_mul_hi_u32 s30, s31, s30
	s_add_i32 s31, s31, s30
	s_mul_hi_u32 s30, s18, s31
	s_mul_i32 s31, s30, s26
	s_sub_i32 s18, s18, s31
	s_add_i32 s34, s30, 1
	s_sub_i32 s31, s18, s26
	s_cmp_ge_u32 s18, s26
	s_cselect_b32 s30, s34, s30
	s_cselect_b32 s18, s31, s18
	s_add_i32 s31, s30, 1
	s_cmp_ge_u32 s18, s26
	s_cselect_b32 s18, s31, s30
	s_xor_b32 s18, s18, s27
	s_sub_i32 s26, s18, s27
	s_mul_i32 s18, s26, s21
	s_sub_i32 s17, s17, s18
	s_add_i32 s17, s17, s19
	s_and_b64 s[18:19], s[4:5], exec
	s_cselect_b32 s17, s26, s17
	v_lshl_add_u32 v14, s17, 8, v12
	v_ashrrev_i32_e32 v15, 31, v14
	v_lshl_add_u64 v[14:15], v[14:15], 2, s[0:1]
	global_load_dword v134, v[14:15], off

.LBB0_108:
	v_cvt_f32_u32_e32 v11, s10
	s_sub_i32 s11, 0, s10
	s_ashr_i32 s8, s8, 3
	s_add_i32 s8, s9, s8
	v_rcp_iflag_f32_e32 v11, v11
	s_abs_i32 s12, s8
	s_ashr_i32 s9, s8, 31
	v_mul_f32_e32 v11, 0x4f7ffffe, v11
	v_cvt_u32_f32_e32 v11, v11
	s_nop 0
	v_readfirstlane_b32 s13, v11
	s_mul_i32 s11, s11, s13
	s_mul_hi_u32 s11, s13, s11
	s_add_i32 s13, s13, s11
	s_mul_hi_u32 s11, s12, s13
	s_mul_i32 s13, s11, s10
	s_sub_i32 s12, s12, s13
	s_add_i32 s16, s11, 1
	s_sub_i32 s13, s12, s10
	s_cmp_ge_u32 s12, s10
	s_cselect_b32 s11, s16, s11
	s_cselect_b32 s12, s13, s12
	s_add_i32 s13, s11, 1
	s_cmp_ge_u32 s12, s10
	s_cselect_b32 s11, s13, s11
	s_xor_b32 s11, s11, s9
	s_sub_i32 s9, s11, s9
	s_lshl_b32 s11, s9, 3
	s_sub_i32 s12, s88, s11
	s_min_i32 s12, s12, 8
	s_abs_i32 s13, s12
	v_cvt_f32_u32_e32 v11, s13
	s_sub_i32 s16, 0, s13
	s_mul_i32 s9, s9, s10
	s_sub_i32 s8, s8, s9
	v_rcp_iflag_f32_e32 v11, v11
	s_abs_i32 s9, s8
	s_xor_b32 s10, s8, s12
	s_ashr_i32 s10, s10, 31
	v_mul_f32_e32 v11, 0x4f7ffffe, v11
	v_cvt_u32_f32_e32 v11, v11
	s_nop 0
	v_readfirstlane_b32 s17, v11
	s_mul_i32 s16, s16, s17
	s_mul_hi_u32 s16, s17, s16
	s_add_i32 s17, s17, s16
	s_mul_hi_u32 s16, s9, s17
	s_mul_i32 s17, s16, s13
	s_sub_i32 s9, s9, s17
	s_add_i32 s18, s16, 1
	s_sub_i32 s17, s9, s13
	s_cmp_ge_u32 s9, s13
	s_cselect_b32 s16, s18, s16
	s_cselect_b32 s9, s17, s9
	s_add_i32 s17, s16, 1
	s_cmp_ge_u32 s9, s13
	s_cselect_b32 s9, s17, s16
	s_xor_b32 s9, s9, s10
	s_sub_i32 s9, s9, s10
	s_mul_i32 s10, s9, s12
	s_sub_i32 s8, s8, s10
	s_add_i32 s8, s8, s11
	s_and_b64 s[4:5], s[4:5], exec
	s_cselect_b32 s4, s9, s8
	v_lshl_add_u32 v14, s4, 8, v12
	v_ashrrev_i32_e32 v15, 31, v14
	v_lshl_add_u64 v[14:15], v[14:15], 2, s[0:1]
	global_load_dword v135, v[14:15], off
	s_mov_b32 s0, 0x800000

.LBB0_110:
	s_waitcnt vmcnt(0)
	s_mov_b64 vcc, exec
	s_and_b64 exec, exec, s[36:37]
	v_fmamk_f32 v128, v128, 0x3a800000, v224
	v_fmamk_f32 v129, v129, 0x3a800000, v224
	v_fmamk_f32 v130, v130, 0x3a800000, v224
	v_fmamk_f32 v131, v131, 0x3a800000, v224
	v_fmamk_f32 v132, v132, 0x3a800000, v224
	v_fmamk_f32 v133, v133, 0x3a800000, v224
	v_fmamk_f32 v134, v134, 0x3a800000, v224
	v_fmamk_f32 v135, v135, 0x3a800000, v224
	v_rsq_f32_e32 v128, v128
	v_rsq_f32_e32 v129, v129
	v_rsq_f32_e32 v130, v130
	v_rsq_f32_e32 v131, v131
	v_rsq_f32_e32 v132, v132
	v_rsq_f32_e32 v133, v133
	v_rsq_f32_e32 v134, v134
	v_rsq_f32_e32 v135, v135
	ds_write_b32 v10, v128
	ds_write_b32 v10, v129 offset:1024
	ds_write_b32 v10, v130 offset:2048
	ds_write_b32 v10, v131 offset:3072
	ds_write_b32 v10, v132 offset:4096
	ds_write_b32 v10, v133 offset:5120
	ds_write_b32 v10, v134 offset:6144
	ds_write_b32 v10, v135 offset:7168
	s_mov_b64 exec, vcc
	s_waitcnt vmcnt(0) lgkmcnt(0)
	s_barrier
